# diff-attn side-job item path: first S-tile MFMA of the next step issued right after the item LDS reads (gain temps renamed)
# speedup vs baseline: 1.0006x; 1.0006x over previous
; __device__ __forceinline__ void side_drain(const SideJob& J, int i, int tid, char* lds) {
;   const SideItem t = side_item(J, i);
;   const int n = tid >> 3, kc = tid & 7;
;   const float* R = (const float*)(lds + LDS_SJ_R + (i & 1) * 16384) + (8 * kc) * 64 + 4 * ((n >> 2) ^ kc) + (n & 3);
;   float v[8];
; #pragma unroll
;   for (int j = 0; j < 8; ++j) v[j] = R[j * 64];
.LBB0_421:
	s_andn2_b64 vcc, exec, s[28:29]
	s_cbranch_vccnz .LBB0_432
	s_lshl_b32 s98, s88, 14
	s_and_b32 s98, s98, 0x4000
	v_add_u32_e32 v86, s98, v198
	ds_read2st64_b32 v[92:93], v86 offset1:1
	ds_read2st64_b32 v[90:91], v86 offset0:2 offset1:3
	ds_read2st64_b32 v[88:89], v86 offset0:4 offset1:5
	ds_read2st64_b32 v[86:87], v86 offset0:6 offset1:7
	v_add_f32_e32 v232, v98, v99
	v_cvt_pk_bf16_f32 v126, v98, v99
	v_mfma_f32_32x32x16_bf16 v[98:113], v[82:85], v[244:247], v[66:81]
	s_lshl_b32 s53, s88, 8
	s_add_i32 s53, s53, s76
	s_cmpk_gt_i32 s53, 0x3ff
	s_mov_b64 s[38:39], -1
	s_cbranch_scc0 .LBB0_427
	s_lshl_b32 s73, s53, 6
	s_cmpk_gt_u32 s53, 0x13ff
	s_mov_b64 s[28:29], -1
	s_cbranch_scc0 .LBB0_425
	s_lshl_b32 s28, s53, 1
	s_add_i32 s28, s28, 0x7fffd800
	s_and_b32 s40, s28, 0x7fffffc0
	s_and_b32 s41, s73, 0x7c0
	s_mov_b64 s[28:29], 0

; __device__ __forceinline__ unsigned cvtpk(float lo, float hi) { unsigned r; asm volatile("v_cvt_pk_bf16_f32 %0, %1, %2" : "=v"(r) : "v"(lo), "v"(hi)); return r; }
; __device__ __forceinline__ void side_drain(const SideJob& J, int i, int tid, char* lds) {
;     ...
;   if (t.gain) { const float* gl = (const float*)(lds + LDS_SJ_G) + t.k0 + 8 * kc;
; #pragma unroll
;     for (int j = 0; j < 8; ++j) v[j] *= gl[j]; }
;   u32x4 o; o.x = cvtpk(v[0], v[1]); o.y = cvtpk(v[2], v[3]); o.z = cvtpk(v[4], v[5]); o.w = cvtpk(v[6], v[7]);
;   *(u32x4*)(t.WT + (((unsigned)(t.n0 + n) << t.lgK) + (unsigned)(t.k0 + 8 * kc))) = o;
.LBB0_429:
	s_lshl_b32 s38, s88, 14
	s_and_b32 s38, s38, 0x4000
	s_andn2_b64 vcc, exec, s[36:37]
	s_cbranch_vccnz .LBB0_431
	v_lshl_add_u32 v233, s40, 2, v200
	ds_read_b128 v[94:97], v233
	ds_read_b128 v[236:239], v233 offset:16
	s_waitcnt lgkmcnt(1)
	v_pk_mul_f32 v[92:93], v[92:93], v[94:95]
	v_pk_mul_f32 v[90:91], v[90:91], v[96:97]
	s_waitcnt lgkmcnt(0)
	v_pk_mul_f32 v[88:89], v[88:89], v[236:237]
	v_pk_mul_f32 v[86:87], v[86:87], v[238:239]
.LBB0_431:
	s_waitcnt lgkmcnt(3)
	v_cvt_pk_bf16_f32 v92, v92, v93
	s_waitcnt lgkmcnt(2)
	v_cvt_pk_bf16_f32 v93, v90, v91
	s_waitcnt lgkmcnt(1)
	v_cvt_pk_bf16_f32 v94, v88, v89
	s_waitcnt lgkmcnt(0)
	v_cvt_pk_bf16_f32 v95, v86, v87
	v_add_u32_e32 v86, s41, v197
	v_or_b32_e32 v87, s40, v199
	v_lshl_add_u32 v146, v86, s52, v87
	v_lshl_add_u64 v[86:87], v[146:147], 1, s[28:29]
	s_add_i32 s88, s88, 1
	global_store_dwordx4 v[86:87], v[92:95], off
	ds_read_b128 v[228:231], v118 offset:2560
	v_add_u32_e32 v205, s0, v192
	v_mov_b32_e32 v86, v232
	s_branch .Lsj_join

; __device__ __forceinline__ SideItem side_item(const SideJob& J, int i) {
;   int gi = J.first + J.stride * i; SideItem t;
;   if (gi < 1024) { t.W = J.w_out; t.WT = J.WOUT; t.K = 2048; t.N = 2048; t.lgK = 11; t.lgN = 11; t.k0 = 64 * (gi >> 5); t.n0 = 64 * (gi & 31); t.gain = false; }
;   else if (gi < 5120) { gi -= 1024; t.W = J.w_up; t.WT = J.WUP; t.K = 2048; t.N = 8192; t.lgK = 11; t.lgN = 13; t.k0 = 64 * (gi >> 7); t.n0 = 64 * (gi & 127); t.gain = true; }
;   else { gi -= 5120; t.W = J.w_dn; t.WT = J.WDN; t.K = 8192; t.N = 2048; t.lgK = 13; t.lgN = 11; t.k0 = 64 * (gi >> 5); t.n0 = 64 * (gi & 31); t.gain = false; }
.Lsj_join:
	v_add_f32_e32 v86, v86, v127
	v_add_f32_e32 v86, v86, v206
	v_add_f32_e32 v86, v86, v142
	v_add_f32_e32 v86, v86, v144
	v_cvt_pk_bf16_f32 v127, v127, v206
	ds_read_b128 v[236:239], v118 offset:4096
	v_add_f32_e32 v82, v210, v86
	v_add_f32_e32 v82, v212, v82
	v_add_f32_e32 v82, v143, v82
	v_add_f32_e32 v114, v122, v82
	v_mfma_f32_32x32x16_bf16 v[82:97], v[130:133], v[244:247], v[66:81]
	v_cvt_pk_bf16_f32 v128, v142, v144
	v_cvt_pk_bf16_f32 v129, v210, v212
	ds_read_b128 v[130:133], v118 offset:4608
	s_waitcnt lgkmcnt(2)
	v_mfma_f32_32x32x16_bf16 v[98:113], v[134:137], v[248:251], v[98:113]
	v_add_f32_e32 v114, v123, v114
	v_add_f32_e32 v114, v209, v114
	v_add_f32_e32 v114, v208, v114
	v_add_f32_e32 v114, v211, v114
	v_cvt_pk_bf16_f32 v122, v143, v122
	v_cvt_pk_bf16_f32 v123, v123, v209
	ds_read_b128 v[134:137], v118 offset:6144
	v_mfma_f32_32x32x16_bf16 v[82:97], v[228:231], v[248:251], v[82:97]
	v_add_f32_e32 v114, v203, v114
	v_add_f32_e32 v114, v220, v114
	v_add_f32_e32 v114, v204, v114
	v_add_f32_e32 v114, v207, v114
	v_cvt_pk_bf16_f32 v124, v208, v211
	v_cvt_pk_bf16_f32 v125, v203, v220
	ds_read_b128 v[208:211], v118 offset:6656
	ds_read_b128 v[228:231], v201 offset:3072
	s_waitcnt lgkmcnt(3)
	v_mfma_f32_32x32x16_bf16 v[98:113], v[236:239], v[252:255], v[98:113]
	v_add_f32_e32 v114, v216, v114
	v_add_f32_e32 v114, v218, v114
	v_add_f32_e32 v114, v145, v114
	v_add_f32_e32 v114, v219, v114
	v_cvt_pk_bf16_f32 v118, v204, v207
	v_cvt_pk_bf16_f32 v119, v216, v218
	ds_read_b64_tr_b16 v[232:233], v205 offset:32768
	ds_read_b64_tr_b16 v[234:235], v205 offset:33280
	v_mfma_f32_32x32x16_bf16 v[82:97], v[130:133], v[252:255], v[82:97]
	v_add_f32_e32 v114, v213, v114
	v_add_f32_e32 v114, v214, v114
	v_add_f32_e32 v114, v215, v114
	v_add_f32_e32 v114, v217, v114
	v_cvt_pk_bf16_f32 v120, v145, v219
	v_cvt_pk_bf16_f32 v121, v213, v214
	ds_read_b64_tr_b16 v[138:139], v205 offset:36864
	ds_read_b64_tr_b16 v[140:141], v205 offset:37376
	s_waitcnt lgkmcnt(4)
	v_mfma_f32_32x32x16_bf16 v[98:113], v[134:137], v[228:231], v[98:113]
	v_add_f32_e32 v114, v221, v114
	v_add_f32_e32 v114, v223, v114
	v_add_f32_e32 v114, v222, v114
	v_add_f32_e32 v130, v224, v114
	v_cvt_pk_bf16_f32 v114, v215, v217
	v_cvt_pk_bf16_f32 v115, v221, v223
	ds_read_b64_tr_b16 v[142:143], v205 offset:40960
	ds_read_b64_tr_b16 v[144:145], v205 offset:41472
	v_mfma_f32_32x32x16_bf16 v[82:97], v[208:211], v[228:231], v[82:97]
	v_add_f32_e32 v116, v225, v130
	v_add_f32_e32 v130, v226, v116
	v_cvt_pk_bf16_f32 v116, v222, v224
	v_cvt_pk_bf16_f32 v117, v225, v226
	s_waitcnt lgkmcnt(4)
	v_mfma_f32_32x32x16_bf16 v[2:17], v[126:129], v[232:235], v[2:17]
	ds_read_b64_tr_b16 v[134:135], v205 offset:45056
	ds_read_b64_tr_b16 v[136:137], v205 offset:45568
	s_cmp_lt_i32 s88, s3
	s_cselect_b64 s[28:29], -1, 0
	s_cmp_ge_i32 s88, s3
	s_cselect_b64 s[36:37], -1, 0
	s_and_b64 vcc, exec, s[36:37]
	s_cbranch_vccnz .LBB0_442
	s_lshl_b32 s0, s88, 8
	s_add_i32 s0, s0, s76
	s_cmpk_gt_i32 s0, 0x3ff
	s_cbranch_scc0 .LBB0_436
	s_lshl_b32 s82, s0, 6
	s_cmpk_gt_u32 s0, 0x13ff
	s_cbranch_scc0 .LBB0_437
	s_lshl_b32 s38, s0, 1
	s_add_i32 s38, s38, 0x7fffd800
	s_and_b32 s52, s38, 0x7fffffc0
	s_and_b32 s53, s82, 0x7c0
	s_mov_b64 s[38:39], s[64:65]
	s_mov_b32 s73, 11
	s_cbranch_execz .LBB0_438
	s_branch .LBB0_439
